# v46 plus: weight-conversion prologue keeps the next item's loads in flight through the whole LDS transpose/store phase (8-step vmcnt ladder replaced by one pre-loop wait and one counted wait before th
# baseline (speedup 1.0000x reference)
.LBB0_32:
	s_and_b64 vcc, exec, s[6:7]
	s_lshl_b32 s84, s98, 3
	s_cbranch_vccnz .LBB0_67
	s_lshl_b32 s6, s33, 14
	s_add_i32 s6, s6, 0
	v_and_b32_e32 v35, 7, v218
	v_mov_b32_e32 v89, 0
	v_lshl_add_u32 v36, v35, 4, s6
	v_mul_u32_u24_e32 v37, 0x84, v68
	v_lshlrev_b32_e32 v34, 3, v35
	v_mul_u32_u24_e32 v35, 0x420, v35
	v_lshlrev_b32_e32 v38, 2, v68
	v_and_b32_e32 v86, 28, v66
	v_or_b32_e32 v1, 8, v68
	v_or_b32_e32 v67, 16, v68
	v_or_b32_e32 v71, 24, v68
	v_or_b32_e32 v73, 32, v68
	v_or_b32_e32 v75, 40, v68
	v_or_b32_e32 v77, 48, v68
	v_or_b32_e32 v79, 56, v68
	v_add3_u32 v81, s6, v35, v38
	v_mov_b32_e32 v69, v89
	v_add_u32_e32 v83, v36, v37
	v_lshlrev_b32_e32 v90, 1, v34
	s_mov_b32 s23, s58
	s_mov_b32 s28, s22
	s_mov_b32 s26, s20
	s_mov_b64 s[8:9], s[18:19]
	s_mov_b32 s44, s43
	s_waitcnt vmcnt(0)
	s_branch .LBB0_35

.LBB0_60:
	v_pk_mul_f32 v[98:99], v[72:73], v[2:3] op_sel_hi:[0,1]
	ds_write2_b32 v83, v98, v99 offset1:1
	v_pk_mul_f32 v[98:99], v[72:73], v[4:5] op_sel_hi:[0,1]
	ds_write2_b32 v83, v98, v99 offset0:2 offset1:3
	v_pk_mul_f32 v[98:99], v[70:71], v[6:7] op_sel_hi:[0,1]
	v_add_u32_e32 v88, 0x420, v83
	ds_write2_b32 v88, v98, v99 offset1:1
	v_pk_mul_f32 v[98:99], v[70:71], v[8:9] op_sel_hi:[0,1]
	v_add_u32_e32 v88, 0x428, v83
	ds_write2_b32 v88, v98, v99 offset1:1
	v_pk_mul_f32 v[98:99], v[76:77], v[10:11] op_sel_hi:[0,1]
	v_add_u32_e32 v88, 0x840, v83
	ds_write2_b32 v88, v98, v99 offset1:1
	v_pk_mul_f32 v[98:99], v[76:77], v[12:13] op_sel_hi:[0,1]
	v_add_u32_e32 v88, 0x848, v83
	ds_write2_b32 v88, v98, v99 offset1:1
	v_pk_mul_f32 v[98:99], v[74:75], v[14:15] op_sel_hi:[0,1]
	v_add_u32_e32 v88, 0xc60, v83
	ds_write2_b32 v88, v98, v99 offset1:1
	v_pk_mul_f32 v[98:99], v[74:75], v[16:17] op_sel_hi:[0,1]
	v_add_u32_e32 v88, 0xc68, v83
	ds_write2_b32 v88, v98, v99 offset1:1
	v_pk_mul_f32 v[98:99], v[80:81], v[18:19] op_sel_hi:[0,1]
	v_add_u32_e32 v88, 0x1080, v83
	ds_write2_b32 v88, v98, v99 offset1:1
	v_pk_mul_f32 v[98:99], v[80:81], v[20:21] op_sel_hi:[0,1]
	v_add_u32_e32 v88, 0x1088, v83
	ds_write2_b32 v88, v98, v99 offset1:1
	v_pk_mul_f32 v[98:99], v[78:79], v[22:23] op_sel_hi:[0,1]
	v_add_u32_e32 v88, 0x14a0, v83
	ds_write2_b32 v88, v98, v99 offset1:1
	v_pk_mul_f32 v[98:99], v[78:79], v[24:25] op_sel_hi:[0,1]
	v_add_u32_e32 v88, 0x14a8, v83
	ds_write2_b32 v88, v98, v99 offset1:1
	v_pk_mul_f32 v[98:99], v[84:85], v[26:27] op_sel_hi:[0,1]
	v_add_u32_e32 v88, 0x18c0, v83
	ds_write2_b32 v88, v98, v99 offset1:1
	v_pk_mul_f32 v[98:99], v[84:85], v[28:29] op_sel_hi:[0,1]
	v_add_u32_e32 v88, 0x18c8, v83
	ds_write2_b32 v88, v98, v99 offset1:1
	v_pk_mul_f32 v[98:99], v[82:83], v[30:31] op_sel_hi:[0,1]
	v_add_u32_e32 v88, 0x1ce0, v83
	ds_write2_b32 v88, v98, v99 offset1:1
	v_pk_mul_f32 v[98:99], v[82:83], v[32:33] op_sel_hi:[0,1]
	v_add_u32_e32 v88, 0x1ce8, v83
	ds_write2_b32 v88, v98, v99 offset1:1
	v_add_u32_e32 v88, s22, v68
	s_waitcnt lgkmcnt(0)
	v_mad_u64_u32 v[118:119], s[6:7], v88, s43, 0
	ds_read2_b32 v[102:103], v81 offset0:33 offset1:41
	ds_read2_b32 v[104:105], v81 offset1:8
	ds_read2_b32 v[106:107], v81 offset0:66 offset1:74
	ds_read2_b32 v[108:109], v81 offset0:99 offset1:107
	ds_read2_b32 v[110:111], v81 offset0:132 offset1:140
	ds_read2_b32 v[112:113], v81 offset0:165 offset1:173
	ds_read2_b32 v[114:115], v81 offset0:198 offset1:206
	ds_read2_b32 v[116:117], v81 offset0:231 offset1:239
	v_ashrrev_i32_e32 v91, 31, v88
	v_mov_b32_e32 v88, v119
	v_mad_u64_u32 v[120:121], s[6:7], v91, s43, v[88:89]
	v_mov_b32_e32 v119, v120
	s_ashr_i32 s21, s20, 31
	v_lshl_add_u64 v[118:119], v[118:119], 1, s[18:19]
	s_lshl_b64 s[6:7], s[20:21], 1
	v_lshl_add_u64 v[118:119], v[118:119], 0, s[6:7]
	v_mov_b32_e32 v91, v89
	s_waitcnt lgkmcnt(6)
	v_cvt_pk_bf16_f32 v98, v104, v102
	s_waitcnt lgkmcnt(4)
	v_cvt_pk_bf16_f32 v99, v106, v108
	s_waitcnt lgkmcnt(2)
	v_cvt_pk_bf16_f32 v100, v110, v112
	s_waitcnt lgkmcnt(0)
	v_cvt_pk_bf16_f32 v101, v114, v116
	v_lshl_add_u64 v[118:119], v[118:119], 0, v[90:91]
	v_add_u32_e32 v88, s22, v1
	global_store_dwordx4 v[118:119], v[98:101], off
	v_ashrrev_i32_e32 v104, 31, v88
	s_andn2_b64 vcc, exec, s[30:31]
	v_cvt_pk_bf16_f32 v98, v105, v103
	v_mad_u64_u32 v[102:103], s[34:35], v88, s43, 0
	v_mov_b32_e32 v88, v103
	v_mad_u64_u32 v[104:105], s[34:35], v104, s43, v[88:89]
	v_mov_b32_e32 v103, v104
	v_lshl_add_u64 v[102:103], v[102:103], 1, s[18:19]
	v_lshl_add_u64 v[102:103], v[102:103], 0, s[6:7]
	v_cvt_pk_bf16_f32 v99, v107, v109
	v_cvt_pk_bf16_f32 v100, v111, v113
	v_cvt_pk_bf16_f32 v101, v115, v117
	v_lshl_add_u64 v[102:103], v[102:103], 0, v[90:91]
	v_add_u32_e32 v88, s22, v67
	ds_read2_b32 v[104:105], v81 offset0:16 offset1:24
	ds_read2_b32 v[106:107], v81 offset0:49 offset1:57
	ds_read2_b32 v[108:109], v81 offset0:82 offset1:90
	ds_read2_b32 v[110:111], v81 offset0:115 offset1:123
	ds_read2_b32 v[112:113], v81 offset0:148 offset1:156
	ds_read2_b32 v[114:115], v81 offset0:181 offset1:189
	ds_read2_b32 v[116:117], v81 offset0:214 offset1:222
	ds_read2_b32 v[118:119], v81 offset0:247 offset1:255
	global_store_dwordx4 v[102:103], v[98:101], off
	v_mad_u64_u32 v[102:103], s[34:35], v88, s43, 0
	s_waitcnt lgkmcnt(6)
	v_cvt_pk_bf16_f32 v98, v104, v106
	v_ashrrev_i32_e32 v104, 31, v88
	v_mov_b32_e32 v88, v103
	v_mad_u64_u32 v[120:121], s[34:35], v104, s43, v[88:89]
	v_mov_b32_e32 v103, v120
	v_lshl_add_u64 v[102:103], v[102:103], 1, s[18:19]
	v_lshl_add_u64 v[102:103], v[102:103], 0, s[6:7]
	s_waitcnt lgkmcnt(4)
	v_cvt_pk_bf16_f32 v99, v108, v110
	s_waitcnt lgkmcnt(2)
	v_cvt_pk_bf16_f32 v100, v112, v114
	s_waitcnt lgkmcnt(0)
	v_cvt_pk_bf16_f32 v101, v116, v118
	v_lshl_add_u64 v[102:103], v[102:103], 0, v[90:91]
	v_add_u32_e32 v88, s22, v71
	global_store_dwordx4 v[102:103], v[98:101], off
	v_mad_u64_u32 v[102:103], s[34:35], v88, s43, 0
	v_ashrrev_i32_e32 v104, 31, v88
	v_mov_b32_e32 v88, v103
	v_cvt_pk_bf16_f32 v98, v105, v107
	v_mad_u64_u32 v[104:105], s[34:35], v104, s43, v[88:89]
	v_mov_b32_e32 v103, v104
	v_lshl_add_u64 v[102:103], v[102:103], 1, s[18:19]
	v_lshl_add_u64 v[102:103], v[102:103], 0, s[6:7]
	v_cvt_pk_bf16_f32 v99, v109, v111
	v_cvt_pk_bf16_f32 v100, v113, v115
	v_cvt_pk_bf16_f32 v101, v117, v119
	v_lshl_add_u64 v[102:103], v[102:103], 0, v[90:91]
	global_store_dwordx4 v[102:103], v[98:101], off
	s_waitcnt lgkmcnt(0)
	s_cbranch_vccnz .LBB0_34
	s_waitcnt vmcnt(4)
	s_mov_b64 s[18:19], s[8:9]
	s_mov_b32 s43, s44
	s_mov_b32 s20, s26
	s_mov_b32 s22, s28
	v_mov_b32_e32 v72, v85
	v_mov_b32_e32 v70, v87
	v_mov_b32_e32 v76, v92
	v_mov_b32_e32 v74, v93
	v_mov_b32_e32 v80, v94
	v_mov_b32_e32 v78, v95
	v_mov_b32_e32 v84, v96
	v_mov_b32_e32 v82, v97
	v_mov_b32_e32 v2, v34
	v_mov_b32_e32 v3, v35
	v_mov_b32_e32 v4, v36
	v_mov_b32_e32 v5, v37
	v_mov_b32_e32 v6, v42
	v_mov_b32_e32 v7, v43
	v_mov_b32_e32 v8, v44
	v_mov_b32_e32 v9, v45
	v_mov_b32_e32 v10, v38
	v_mov_b32_e32 v11, v39
	v_mov_b32_e32 v12, v40
	v_mov_b32_e32 v13, v41
	v_mov_b32_e32 v14, v46
	v_mov_b32_e32 v15, v47
	v_mov_b32_e32 v16, v48
	v_mov_b32_e32 v17, v49
	v_mov_b32_e32 v18, v50
	v_mov_b32_e32 v19, v51
	v_mov_b32_e32 v20, v52
	v_mov_b32_e32 v21, v53
	v_mov_b32_e32 v22, v54
	v_mov_b32_e32 v23, v55
	v_mov_b32_e32 v24, v56
	v_mov_b32_e32 v25, v57
	v_mov_b32_e32 v26, v58
	v_mov_b32_e32 v27, v59
	v_mov_b32_e32 v28, v60
	v_mov_b32_e32 v29, v61
	v_mov_b32_e32 v30, v62
	v_mov_b32_e32 v31, v63
	v_mov_b32_e32 v32, v64
	v_mov_b32_e32 v33, v65
	s_branch .LBB0_34
